# MLA loop: two instructions between the last v_cvt_pk of the second-half probabilities and the MFMA that reads them (VALU->MFMA wait states per ISA table); otherwise as v92
# baseline (speedup 1.0000x reference)
; #define MFMA(a, b, c) __builtin_amdgcn_mfma_f32_32x32x16_bf16((a), (b), (c), 0, 0, 0)
; DI unsigned pk2(float a, float b) { f2_t v = {a, b}; bf2_t r = __builtin_convertvector(v, bf2_t); return __builtin_bit_cast(unsigned, r); }
; DI float xhalf_sum(float x) { const auto rr = __builtin_amdgcn_permlane32_swap(__float_as_uint(x), __float_as_uint(x), false, false); return __uint_as_float(rr[0]) + __uint_as_float(rr[1]); }
; template <int DQK, int DV, bool BAND> ...
;     ...
;       const float m_ref = (m_run == -INFINITY) ? 0.f : m_run;
;       float rs0 = 0.f, rs1 = 0.f;
; #pragma unroll
;       for (int r = 0; r < 16; ++r) { const float e0 = __builtin_amdgcn_exp2f(p0[r] - m_ref), e1 = __builtin_amdgcn_exp2f(p1[r] - m_ref); p0[r] = e0; p1[r] = e1; rs0 += e0; rs1 += e1; }
;       l_run += xhalf_sum(rs0 + rs1);
;       __builtin_amdgcn_s_setprio(1);
; #pragma unroll
;       for (int s = 0; s < 2; ++s) {
;         const u32x4 pu0 = {pk2(p0[8 * s], p0[8 * s + 1]), pk2(p0[8 * s + 2], p0[8 * s + 3]), pk2(p0[8 * s + 4], p0[8 * s + 5]), pk2(p0[8 * s + 6], p0[8 * s + 7])};
;         const u32x4 pu1 = {pk2(p1[8 * s], p1[8 * s + 1]), pk2(p1[8 * s + 2], p1[8 * s + 3]), pk2(p1[8 * s + 4], p1[8 * s + 5]), pk2(p1[8 * s + 6], p1[8 * s + 7])};
; #pragma unroll
;         for (int cb = 0; cb < NCB; ++cb) {
;           const u32x2 lo0 = *(const u32x2*)&Vs[(cb * 32 + r32) * VLD + 16 * s + 4 * hi];
;           const u32x2 hi0 = *(const u32x2*)&Vs[(cb * 32 + r32) * VLD + 16 * s + 4 * hi + 8];
;           const u32x4 v0 = {lo0[0], lo0[1], hi0[0], hi0[1]};
;           o[cb] = MFMA(__builtin_bit_cast(bf16x8, pu0), __builtin_bit_cast(bf16x8, v0), o[cb]);
;         }
; #pragma unroll
;         for (int cb = 0; cb < NCB; ++cb) {
;           const u32x2 lo1 = *(const u32x2*)&Vs[(cb * 32 + r32) * VLD + 32 + 16 * s + 4 * hi];
;           const u32x2 hi1 = *(const u32x2*)&Vs[(cb * 32 + r32) * VLD + 32 + 16 * s + 4 * hi + 8];
;           const u32x4 v1 = {lo1[0], lo1[1], hi1[0], hi1[1]};
;           o[cb] = MFMA(__builtin_bit_cast(bf16x8, pu1), __builtin_bit_cast(bf16x8, v1), o[cb]);
;         }
;       }
;       __builtin_amdgcn_s_setprio(0);
.LBB1_325:
	v_exp_f32_e32 v34, v34
	v_exp_f32_e32 v35, v35
	v_exp_f32_e32 v36, v36
	v_exp_f32_e32 v37, v37
	v_exp_f32_e32 v38, v38
	v_exp_f32_e32 v39, v39
	v_exp_f32_e32 v40, v40
	v_exp_f32_e32 v41, v41
	v_exp_f32_e32 v42, v42
	v_exp_f32_e32 v43, v43
	v_exp_f32_e32 v44, v44
	v_exp_f32_e32 v45, v45
	v_exp_f32_e32 v46, v46
	v_exp_f32_e32 v47, v47
	v_exp_f32_e32 v48, v48
	v_exp_f32_e32 v49, v49
	s_nop 0
	v_pk_add_f32 v[168:169], v[34:35], v[36:37]
	v_pk_add_f32 v[170:171], v[38:39], v[40:41]
	v_pk_add_f32 v[168:169], v[42:43], v[168:169]
	v_pk_add_f32 v[170:171], v[44:45], v[170:171]
	v_pk_add_f32 v[168:169], v[46:47], v[168:169]
	v_pk_add_f32 v[170:171], v[48:49], v[170:171]
	v_cvt_pk_bf16_f32 v34, v34, v35
	v_cvt_pk_bf16_f32 v35, v36, v37
	v_cvt_pk_bf16_f32 v36, v38, v39
	v_cvt_pk_bf16_f32 v37, v40, v41
	v_cvt_pk_bf16_f32 v38, v42, v43
	v_cvt_pk_bf16_f32 v39, v44, v45
	v_cvt_pk_bf16_f32 v40, v46, v47
	v_cvt_pk_bf16_f32 v41, v48, v49
	v_exp_f32_e32 v50, v50
	v_exp_f32_e32 v51, v51
	v_exp_f32_e32 v52, v52
	s_waitcnt lgkmcnt(0)
	v_mfma_f32_32x32x16_bf16 v[2:17], v[34:37], v[208:211], v[2:17]
	v_exp_f32_e32 v53, v53
	v_exp_f32_e32 v54, v54
	v_exp_f32_e32 v55, v55
	v_mfma_f32_32x32x16_bf16 v[18:33], v[34:37], v[212:215], v[18:33]
	v_exp_f32_e32 v56, v56
	v_exp_f32_e32 v57, v57
	v_exp_f32_e32 v58, v58
	v_mfma_f32_32x32x16_bf16 v[2:17], v[38:41], v[224:227], v[2:17]
	v_exp_f32_e32 v59, v59
	v_exp_f32_e32 v60, v60
	v_exp_f32_e32 v61, v61
	v_mfma_f32_32x32x16_bf16 v[18:33], v[38:41], v[228:231], v[18:33]
	v_cvt_pk_bf16_f32 v240, v50, v51
	v_cvt_pk_bf16_f32 v241, v52, v53
	v_cvt_pk_bf16_f32 v242, v54, v55
	v_cvt_pk_bf16_f32 v243, v56, v57
	v_exp_f32_e32 v62, v62
	v_exp_f32_e32 v63, v63
	v_mfma_f32_32x32x16_bf16 v[2:17], v[240:243], v[216:219], v[2:17]
	v_exp_f32_e32 v64, v64
	v_exp_f32_e32 v65, v65
	v_mfma_f32_32x32x16_bf16 v[18:33], v[240:243], v[220:223], v[18:33]
	v_pk_add_f32 v[168:169], v[50:51], v[168:169]
	v_pk_add_f32 v[170:171], v[52:53], v[170:171]
	v_pk_add_f32 v[168:169], v[54:55], v[168:169]
	v_pk_add_f32 v[170:171], v[56:57], v[170:171]
	v_pk_add_f32 v[168:169], v[58:59], v[168:169]
	v_pk_add_f32 v[170:171], v[60:61], v[170:171]
	v_pk_add_f32 v[168:169], v[62:63], v[168:169]
	v_pk_add_f32 v[170:171], v[64:65], v[170:171]
	v_pk_add_f32 v[168:169], v[168:169], v[170:171]
	v_cvt_pk_bf16_f32 v54, v58, v59
	v_cvt_pk_bf16_f32 v55, v60, v61
	v_cvt_pk_bf16_f32 v56, v62, v63
	v_cvt_pk_bf16_f32 v57, v64, v65
	v_add_f32_e32 v168, v168, v169
	v_mov_b32_e32 v169, v168
	v_mfma_f32_32x32x16_bf16 v[2:17], v[54:57], v[232:235], v[2:17]
	s_nop 0
	v_permlane32_swap_b32_e32 v168, v169
	v_add_f32_e32 v168, v168, v169
	v_add_f32_e32 v126, v126, v168
	v_mfma_f32_32x32x16_bf16 v[18:33], v[54:57], v[236:239], v[18:33]
	s_add_u32 s12, s12, s8
	s_addc_u32 s13, s13, s9
	s_add_u32 s14, s14, s10
	s_addc_u32 s15, s15, s11
	s_cmp_eq_u32 s75, s21
	s_cbranch_scc1 .LBB1_327
	v_mov_b32_e32 v133, v0
	s_branch .LBB1_318
